# K-loop: loader drops to priority 0 only after its LDS fragment read burst (3 of 4 load segments)
# speedup vs baseline: 1.0163x; 1.0163x over previous
; #define PG8_STAGE(bufoff, gbase, voff) do { _Pragma("unroll") for (int _i = 0; _i < 2; ++_i) \
;         __builtin_amdgcn_global_load_lds((const unsigned*)((const char*)(gbase) + (voff)[_i]), (PG8_LAS unsigned*)(lds + (bufoff) + ldsw + _i * 8192), 16, 0, 0); } while (0)
; #define PG8_LDA(dst, b, h) do { _Pragma("unroll") for (int m = 0; m < 4; ++m) _Pragma("unroll") for (int k = 0; k < 2; ++k) dst[m][k] = *(const PG8_LAS bf16x8*)(lds + PG8_SA(b, h) + aoff + m * 2048 + k * 1024); } while (0)
; #define PG8_LDB(dst, b, h) do { _Pragma("unroll") for (int n = 0; n < 2; ++n) _Pragma("unroll") for (int k = 0; k < 2; ++k) dst[n][k] = *(const PG8_LAS bf16x8*)(lds + PG8_SB(b, h) + boff + n * 2048 + k * 1024); } while (0)
; #define PG8_MMA(ai, bj, At, Bt) do { __builtin_amdgcn_s_setprio(1); _Pragma("unroll") for (int m = 0; m < 4; ++m) _Pragma("unroll") for (int n = 0; n < 2; ++n) _Pragma("unroll") for (int k = 0; k < 2; ++k) \
;         acc[ai][bj][m][n] = __builtin_amdgcn_mfma_f32_16x16x32_bf16(Bt[n][k], At[m][k], acc[ai][bj][m][n], 0, 0, 0); __builtin_amdgcn_s_setprio(0); } while (0)
; #define PG8_WAIT_V(n) asm volatile("s_waitcnt vmcnt(" #n ")" ::: "memory")
; #define PG8_WAIT_L(n) asm volatile("s_waitcnt lgkmcnt(" #n ")" ::: "memory")
; #define PG8_BAR __builtin_amdgcn_s_barrier()
; #define PG8_SCHED __builtin_amdgcn_sched_barrier(0)
; template <class Epi, class Sched, bool ALIGN_EPI = false, bool SP2 = false>
; __device__ __forceinline__ void gemm_phase(PG8_LAS unsigned char* lds, const Gemm g, const Sched& S, const Epi& E) {
;     ...
;         for (int t = 0; t < nt; t += 2) {
;             const bool last = (t == nt - 2);
;             const char* a1 = cA + (size_t)(t + 1) * kstep;
;             const char* a2 = last ? nA : cA + (size_t)(t + 2) * kstep; const char* b2 = last ? nB : cB + (size_t)(t + 2) * kstep;
;             const char* a3 = a2 + kstep; const char* b3 = b2 + kstep;
;             if (last && has_next) S.a_ready(nxt);
;             if constexpr (SP2) {
;             PG8_LDB(B0, 0, 0); PG8_LDB(B1, 0, 1); PG8_SCHED; PG8_LDA(At, 0, 0); PG8_STAGE(PG8_SA(1, 1), a1 + hstep, voffA);
;             PG8_WAIT_V(8); PG8_WAIT_L(0); PG8_BAR; PG8_MMA(0, 0, At, B0); PG8_MMA(0, 1, At, B1); PG8_BAR; PG8_SCHED;
;             PG8_LDA(At, 0, 1); PG8_STAGE(PG8_SB(0, 0), b2, voffB); PG8_STAGE(PG8_SB(0, 1), b2 + hstep, voffB); PG8_STAGE(PG8_SA(0, 0), a2, voffA);
.LBB0_441:
	ds_read_b128 v[130:133], v242
	ds_read_b128 v[134:137], v242 offset:1024
	ds_read_b128 v[138:141], v242 offset:2048
	ds_read_b128 v[142:145], v242 offset:3072
	ds_read_b128 v[146:149], v243
	ds_read_b128 v[150:153], v243 offset:1024
	ds_read_b128 v[154:157], v243 offset:2048
	ds_read_b128 v[158:161], v243 offset:3072
	s_add_i32 s66, 0, 0x10000
	s_add_i32 s67, 0, 0x14000
	v_lshl_add_u64 v[206:207], s[42:43], 0, v[190:191]
	s_add_i32 m0, s93, 0xc000
	ds_read_b128 v[162:165], v230
	ds_read_b128 v[166:169], v230 offset:1024
	ds_read_b128 v[170:173], v230 offset:2048
	ds_read_b128 v[174:177], v230 offset:3072
	ds_read_b128 v[178:181], v230 offset:4096
	ds_read_b128 v[194:197], v230 offset:5120
	ds_read_b128 v[198:201], v230 offset:6144
	ds_read_b128 v[202:205], v230 offset:7168
	s_add_i32 s61, s44, 2
	s_add_u32 s64, s42, 0x80
	s_addc_u32 s45, s43, 0
	s_cmp_eq_u32 s99, s44
	s_cselect_b32 s45, s29, s45
	s_cselect_b32 s44, s28, s64
	s_cselect_b32 s65, s21, s60
	s_cselect_b32 s64, s20, s17
	global_load_lds_dwordx4 v[206:207], off
	s_add_i32 m0, s93, 0xe000
	v_lshl_add_u64 v[206:207], s[42:43], 0, v[192:193]
	global_load_lds_dwordx4 v[206:207], off
	s_setprio 1
	s_waitcnt vmcnt(8) lgkmcnt(0)
	s_barrier
	v_mfma_f32_16x16x32_bf16 v[126:129], v[130:133], v[162:165], v[126:129]
	v_mfma_f32_16x16x32_bf16 v[122:125], v[138:141], v[162:165], v[122:125]
	v_mfma_f32_16x16x32_bf16 v[110:113], v[130:133], v[170:173], v[110:113]
	v_mfma_f32_16x16x32_bf16 v[102:105], v[138:141], v[170:173], v[102:105]
	v_mfma_f32_16x16x32_bf16 v[94:97], v[130:133], v[178:181], v[94:97]
	v_mfma_f32_16x16x32_bf16 v[86:89], v[138:141], v[178:181], v[86:89]
	v_mfma_f32_16x16x32_bf16 v[78:81], v[130:133], v[198:201], v[78:81]
	v_mfma_f32_16x16x32_bf16 v[70:73], v[138:141], v[198:201], v[70:73]
	v_mfma_f32_16x16x32_bf16 v[126:129], v[134:137], v[166:169], v[126:129]
	v_mfma_f32_16x16x32_bf16 v[122:125], v[142:145], v[166:169], v[122:125]
	v_mfma_f32_16x16x32_bf16 v[110:113], v[134:137], v[174:177], v[110:113]
	v_mfma_f32_16x16x32_bf16 v[102:105], v[142:145], v[174:177], v[102:105]
	v_mfma_f32_16x16x32_bf16 v[94:97], v[134:137], v[194:197], v[94:97]
	v_mfma_f32_16x16x32_bf16 v[86:89], v[142:145], v[194:197], v[86:89]
	v_mfma_f32_16x16x32_bf16 v[78:81], v[134:137], v[202:205], v[78:81]
	v_mfma_f32_16x16x32_bf16 v[70:73], v[142:145], v[202:205], v[70:73]
	v_mfma_f32_16x16x32_bf16 v[118:121], v[146:149], v[162:165], v[118:121]
	v_mfma_f32_16x16x32_bf16 v[114:117], v[154:157], v[162:165], v[114:117]
	v_mfma_f32_16x16x32_bf16 v[106:109], v[146:149], v[170:173], v[106:109]
	v_mfma_f32_16x16x32_bf16 v[98:101], v[154:157], v[170:173], v[98:101]
	v_mfma_f32_16x16x32_bf16 v[90:93], v[146:149], v[178:181], v[90:93]
	v_mfma_f32_16x16x32_bf16 v[82:85], v[154:157], v[178:181], v[82:85]
	v_mfma_f32_16x16x32_bf16 v[74:77], v[146:149], v[198:201], v[74:77]
	v_mfma_f32_16x16x32_bf16 v[66:69], v[154:157], v[198:201], v[66:69]
	v_mfma_f32_16x16x32_bf16 v[118:121], v[150:153], v[166:169], v[118:121]
	v_mfma_f32_16x16x32_bf16 v[114:117], v[158:161], v[166:169], v[114:117]
	v_mfma_f32_16x16x32_bf16 v[106:109], v[150:153], v[174:177], v[106:109]
	v_mfma_f32_16x16x32_bf16 v[98:101], v[158:161], v[174:177], v[98:101]
	v_mfma_f32_16x16x32_bf16 v[90:93], v[150:153], v[194:197], v[90:93]
	v_mfma_f32_16x16x32_bf16 v[82:85], v[158:161], v[194:197], v[82:85]
	v_mfma_f32_16x16x32_bf16 v[74:77], v[150:153], v[202:205], v[74:77]
	v_mfma_f32_16x16x32_bf16 v[66:69], v[158:161], v[202:205], v[66:69]
	s_barrier
	ds_read_b128 v[162:165], v230 offset:16384
	ds_read_b128 v[166:169], v230 offset:17408
	ds_read_b128 v[170:173], v230 offset:18432
	ds_read_b128 v[174:177], v230 offset:19456
	ds_read_b128 v[178:181], v230 offset:20480
	ds_read_b128 v[194:197], v230 offset:21504
	ds_read_b128 v[198:201], v230 offset:22528
	ds_read_b128 v[202:205], v230 offset:23552
	s_setprio 0
	s_add_i32 s66, s66, s92
	s_mov_b32 m0, s66
	v_lshl_add_u64 v[206:207], s[64:65], 0, v[184:185]
	global_load_lds_dwordx4 v[206:207], off
	s_add_i32 m0, s66, 0x2000
	v_lshl_add_u64 v[208:209], s[64:65], 0, v[188:189]
	s_add_u32 s64, s64, s26
	s_addc_u32 s65, s65, 0
	s_add_i32 s66, s67, s92
	global_load_lds_dwordx4 v[208:209], off
	v_lshl_add_u64 v[210:211], s[64:65], 0, v[184:185]
	s_mov_b32 m0, s66
	v_lshl_add_u64 v[232:233], s[64:65], 0, v[188:189]
	global_load_lds_dwordx4 v[210:211], off
	s_add_i32 m0, s66, 0x2000
	v_lshl_add_u64 v[234:235], s[44:45], 0, v[182:183]
	global_load_lds_dwordx4 v[232:233], off
	s_mov_b32 m0, s93
	v_lshl_add_u64 v[236:237], s[44:45], 0, v[186:187]
	global_load_lds_dwordx4 v[234:235], off
	s_mov_b32 m0, s94
	s_nop 0
	global_load_lds_dwordx4 v[236:237], off
	s_setprio 1
	s_waitcnt vmcnt(8) lgkmcnt(0)
	s_barrier
; #define PG8_STAGE(bufoff, gbase, voff) do { _Pragma("unroll") for (int _i = 0; _i < 2; ++_i) \
;         __builtin_amdgcn_global_load_lds((const unsigned*)((const char*)(gbase) + (voff)[_i]), (PG8_LAS unsigned*)(lds + (bufoff) + ldsw + _i * 8192), 16, 0, 0); } while (0)
; #define PG8_LDA(dst, b, h) do { _Pragma("unroll") for (int m = 0; m < 4; ++m) _Pragma("unroll") for (int k = 0; k < 2; ++k) dst[m][k] = *(const PG8_LAS bf16x8*)(lds + PG8_SA(b, h) + aoff + m * 2048 + k * 1024); } while (0)
; #define PG8_LDB(dst, b, h) do { _Pragma("unroll") for (int n = 0; n < 2; ++n) _Pragma("unroll") for (int k = 0; k < 2; ++k) dst[n][k] = *(const PG8_LAS bf16x8*)(lds + PG8_SB(b, h) + boff + n * 2048 + k * 1024); } while (0)
; #define PG8_MMA(ai, bj, At, Bt) do { __builtin_amdgcn_s_setprio(1); _Pragma("unroll") for (int m = 0; m < 4; ++m) _Pragma("unroll") for (int n = 0; n < 2; ++n) _Pragma("unroll") for (int k = 0; k < 2; ++k) \
;         acc[ai][bj][m][n] = __builtin_amdgcn_mfma_f32_16x16x32_bf16(Bt[n][k], At[m][k], acc[ai][bj][m][n], 0, 0, 0); __builtin_amdgcn_s_setprio(0); } while (0)
; #define PG8_WAIT_V(n) asm volatile("s_waitcnt vmcnt(" #n ")" ::: "memory")
; #define PG8_WAIT_L(n) asm volatile("s_waitcnt lgkmcnt(" #n ")" ::: "memory")
; #define PG8_BAR __builtin_amdgcn_s_barrier()
; #define PG8_SCHED __builtin_amdgcn_sched_barrier(0)
; template <class Epi, class Sched, bool ALIGN_EPI = false, bool SP2 = false>
; __device__ __forceinline__ void gemm_phase(PG8_LAS unsigned char* lds, const Gemm g, const Sched& S, const Epi& E) {
;     ...
;             PG8_WAIT_V(8); PG8_WAIT_L(0); PG8_BAR; PG8_MMA(1, 0, At, B0); PG8_MMA(1, 1, At, B1); PG8_BAR; PG8_SCHED;
;             PG8_LDB(B0, 1, 0); PG8_LDB(B1, 1, 1); PG8_SCHED; PG8_LDA(At, 1, 0); PG8_STAGE(PG8_SA(0, 1), a2 + hstep, voffA);
;             PG8_WAIT_V(8); PG8_WAIT_L(0); PG8_BAR; PG8_MMA(0, 0, At, B0); PG8_MMA(0, 1, At, B1); PG8_BAR; PG8_SCHED;
	v_mfma_f32_16x16x32_bf16 v[62:65], v[130:133], v[162:165], v[62:65]
	v_mfma_f32_16x16x32_bf16 v[54:57], v[138:141], v[162:165], v[54:57]
	v_mfma_f32_16x16x32_bf16 v[46:49], v[130:133], v[170:173], v[46:49]
	v_mfma_f32_16x16x32_bf16 v[38:41], v[138:141], v[170:173], v[38:41]
	v_mfma_f32_16x16x32_bf16 v[30:33], v[130:133], v[178:181], v[30:33]
	v_mfma_f32_16x16x32_bf16 v[22:25], v[138:141], v[178:181], v[22:25]
	v_mfma_f32_16x16x32_bf16 v[14:17], v[130:133], v[198:201], v[14:17]
	v_mfma_f32_16x16x32_bf16 v[6:9], v[138:141], v[198:201], v[6:9]
	v_mfma_f32_16x16x32_bf16 v[62:65], v[134:137], v[166:169], v[62:65]
	v_mfma_f32_16x16x32_bf16 v[54:57], v[142:145], v[166:169], v[54:57]
	v_mfma_f32_16x16x32_bf16 v[46:49], v[134:137], v[174:177], v[46:49]
	v_mfma_f32_16x16x32_bf16 v[38:41], v[142:145], v[174:177], v[38:41]
	v_mfma_f32_16x16x32_bf16 v[30:33], v[134:137], v[194:197], v[30:33]
	v_mfma_f32_16x16x32_bf16 v[22:25], v[142:145], v[194:197], v[22:25]
	v_mfma_f32_16x16x32_bf16 v[14:17], v[134:137], v[202:205], v[14:17]
	v_mfma_f32_16x16x32_bf16 v[6:9], v[142:145], v[202:205], v[6:9]
	v_mfma_f32_16x16x32_bf16 v[58:61], v[146:149], v[162:165], v[58:61]
	v_mfma_f32_16x16x32_bf16 v[50:53], v[154:157], v[162:165], v[50:53]
	v_mfma_f32_16x16x32_bf16 v[42:45], v[146:149], v[170:173], v[42:45]
	v_mfma_f32_16x16x32_bf16 v[34:37], v[154:157], v[170:173], v[34:37]
	v_mfma_f32_16x16x32_bf16 v[26:29], v[146:149], v[178:181], v[26:29]
	v_mfma_f32_16x16x32_bf16 v[18:21], v[154:157], v[178:181], v[18:21]
	v_mfma_f32_16x16x32_bf16 v[10:13], v[146:149], v[198:201], v[10:13]
	v_mfma_f32_16x16x32_bf16 v[2:5], v[154:157], v[198:201], v[2:5]
	v_mfma_f32_16x16x32_bf16 v[58:61], v[150:153], v[166:169], v[58:61]
	v_mfma_f32_16x16x32_bf16 v[50:53], v[158:161], v[166:169], v[50:53]
	v_mfma_f32_16x16x32_bf16 v[42:45], v[150:153], v[174:177], v[42:45]
	v_mfma_f32_16x16x32_bf16 v[34:37], v[158:161], v[174:177], v[34:37]
	v_mfma_f32_16x16x32_bf16 v[26:29], v[150:153], v[194:197], v[26:29]
	v_mfma_f32_16x16x32_bf16 v[18:21], v[158:161], v[194:197], v[18:21]
	v_mfma_f32_16x16x32_bf16 v[10:13], v[150:153], v[202:205], v[10:13]
	v_mfma_f32_16x16x32_bf16 v[2:5], v[158:161], v[202:205], v[2:5]
	s_barrier
	ds_read_b128 v[162:165], v230 offset:32768
	ds_read_b128 v[166:169], v230 offset:33792
	ds_read_b128 v[170:173], v230 offset:34816
	ds_read_b128 v[174:177], v230 offset:35840
	ds_read_b128 v[178:181], v230 offset:36864
	ds_read_b128 v[194:197], v230 offset:37888
	ds_read_b128 v[198:201], v230 offset:38912
	ds_read_b128 v[202:205], v230 offset:39936
	ds_read_b128 v[130:133], v244
	ds_read_b128 v[134:137], v244 offset:1024
	ds_read_b128 v[138:141], v244 offset:2048
	ds_read_b128 v[142:145], v244 offset:3072
	ds_read_b128 v[146:149], v245
	ds_read_b128 v[150:153], v245 offset:1024
	ds_read_b128 v[154:157], v245 offset:2048
	ds_read_b128 v[158:161], v245 offset:3072
	s_setprio 0
	s_add_i32 s64, 0, 0x18000
	s_add_i32 s65, 0, 0x1c000
	s_add_u32 s44, s44, s26
	s_addc_u32 s45, s45, 0
	s_mov_b32 m0, s95
	v_lshl_add_u64 v[238:239], s[44:45], 0, v[182:183]
	global_load_lds_dwordx4 v[238:239], off
	s_mov_b32 m0, s96
	v_lshl_add_u64 v[238:239], s[44:45], 0, v[186:187]
	global_load_lds_dwordx4 v[238:239], off
	s_setprio 1
	s_waitcnt vmcnt(8) lgkmcnt(0)
	s_barrier
	v_mfma_f32_16x16x32_bf16 v[126:129], v[130:133], v[162:165], v[126:129]
	v_mfma_f32_16x16x32_bf16 v[122:125], v[138:141], v[162:165], v[122:125]
	v_mfma_f32_16x16x32_bf16 v[110:113], v[130:133], v[170:173], v[110:113]
	v_mfma_f32_16x16x32_bf16 v[102:105], v[138:141], v[170:173], v[102:105]
	v_mfma_f32_16x16x32_bf16 v[94:97], v[130:133], v[178:181], v[94:97]
	v_mfma_f32_16x16x32_bf16 v[86:89], v[138:141], v[178:181], v[86:89]
	v_mfma_f32_16x16x32_bf16 v[78:81], v[130:133], v[198:201], v[78:81]
	v_mfma_f32_16x16x32_bf16 v[70:73], v[138:141], v[198:201], v[70:73]
	v_mfma_f32_16x16x32_bf16 v[126:129], v[134:137], v[166:169], v[126:129]
	v_mfma_f32_16x16x32_bf16 v[122:125], v[142:145], v[166:169], v[122:125]
	v_mfma_f32_16x16x32_bf16 v[110:113], v[134:137], v[174:177], v[110:113]
	v_mfma_f32_16x16x32_bf16 v[102:105], v[142:145], v[174:177], v[102:105]
	v_mfma_f32_16x16x32_bf16 v[94:97], v[134:137], v[194:197], v[94:97]
	v_mfma_f32_16x16x32_bf16 v[86:89], v[142:145], v[194:197], v[86:89]
	v_mfma_f32_16x16x32_bf16 v[78:81], v[134:137], v[202:205], v[78:81]
	v_mfma_f32_16x16x32_bf16 v[70:73], v[142:145], v[202:205], v[70:73]
	v_mfma_f32_16x16x32_bf16 v[118:121], v[146:149], v[162:165], v[118:121]
	v_mfma_f32_16x16x32_bf16 v[114:117], v[154:157], v[162:165], v[114:117]
	v_mfma_f32_16x16x32_bf16 v[106:109], v[146:149], v[170:173], v[106:109]
	v_mfma_f32_16x16x32_bf16 v[98:101], v[154:157], v[170:173], v[98:101]
	v_mfma_f32_16x16x32_bf16 v[90:93], v[146:149], v[178:181], v[90:93]
	v_mfma_f32_16x16x32_bf16 v[82:85], v[154:157], v[178:181], v[82:85]
	v_mfma_f32_16x16x32_bf16 v[74:77], v[146:149], v[198:201], v[74:77]
	v_mfma_f32_16x16x32_bf16 v[66:69], v[154:157], v[198:201], v[66:69]
	v_mfma_f32_16x16x32_bf16 v[118:121], v[150:153], v[166:169], v[118:121]
	v_mfma_f32_16x16x32_bf16 v[114:117], v[158:161], v[166:169], v[114:117]
	v_mfma_f32_16x16x32_bf16 v[106:109], v[150:153], v[174:177], v[106:109]
	v_mfma_f32_16x16x32_bf16 v[98:101], v[158:161], v[174:177], v[98:101]
	v_mfma_f32_16x16x32_bf16 v[90:93], v[150:153], v[194:197], v[90:93]
	v_mfma_f32_16x16x32_bf16 v[82:85], v[158:161], v[194:197], v[82:85]
	v_mfma_f32_16x16x32_bf16 v[74:77], v[150:153], v[202:205], v[74:77]
	v_mfma_f32_16x16x32_bf16 v[66:69], v[158:161], v[202:205], v[66:69]
	s_barrier
; #define PG8_STAGE(bufoff, gbase, voff) do { _Pragma("unroll") for (int _i = 0; _i < 2; ++_i) \
;         __builtin_amdgcn_global_load_lds((const unsigned*)((const char*)(gbase) + (voff)[_i]), (PG8_LAS unsigned*)(lds + (bufoff) + ldsw + _i * 8192), 16, 0, 0); } while (0)
; #define PG8_LDA(dst, b, h) do { _Pragma("unroll") for (int m = 0; m < 4; ++m) _Pragma("unroll") for (int k = 0; k < 2; ++k) dst[m][k] = *(const PG8_LAS bf16x8*)(lds + PG8_SA(b, h) + aoff + m * 2048 + k * 1024); } while (0)
; #define PG8_MMA(ai, bj, At, Bt) do { __builtin_amdgcn_s_setprio(1); _Pragma("unroll") for (int m = 0; m < 4; ++m) _Pragma("unroll") for (int n = 0; n < 2; ++n) _Pragma("unroll") for (int k = 0; k < 2; ++k) \
;         acc[ai][bj][m][n] = __builtin_amdgcn_mfma_f32_16x16x32_bf16(Bt[n][k], At[m][k], acc[ai][bj][m][n], 0, 0, 0); __builtin_amdgcn_s_setprio(0); } while (0)
; #define PG8_WAIT_V(n) asm volatile("s_waitcnt vmcnt(" #n ")" ::: "memory")
; #define PG8_WAIT_L(n) asm volatile("s_waitcnt lgkmcnt(" #n ")" ::: "memory")
; #define PG8_BAR __builtin_amdgcn_s_barrier()
; #define PG8_SCHED __builtin_amdgcn_sched_barrier(0)
; template <class Epi, class Sched, bool ALIGN_EPI = false, bool SP2 = false>
; __device__ __forceinline__ void gemm_phase(PG8_LAS unsigned char* lds, const Gemm g, const Sched& S, const Epi& E) {
;     ...
;             PG8_LDA(At, 1, 1); PG8_STAGE(PG8_SB(1, 0), b3, voffB); PG8_STAGE(PG8_SB(1, 1), b3 + hstep, voffB); PG8_STAGE(PG8_SA(1, 0), a3, voffA);
;             PG8_WAIT_V(8); PG8_WAIT_L(0); PG8_BAR; PG8_MMA(1, 0, At, B0); PG8_MMA(1, 1, At, B1); PG8_BAR; PG8_SCHED;
;     ...
;         if constexpr (ALIGN_EPI) { if (wr == 0) PG8_BAR; }
	ds_read_b128 v[162:165], v230 offset:49152
	ds_read_b128 v[166:169], v230 offset:50176
	ds_read_b128 v[170:173], v230 offset:51200
	ds_read_b128 v[174:177], v230 offset:52224
	ds_read_b128 v[178:181], v230 offset:53248
	ds_read_b128 v[194:197], v230 offset:54272
	ds_read_b128 v[198:201], v230 offset:55296
	ds_read_b128 v[202:205], v230 offset:56320
	s_setprio 0
	s_add_i32 s44, s64, s92
	s_mov_b32 m0, s44
	v_lshl_add_u64 v[206:207], v[206:207], 0, s[34:35]
	global_load_lds_dwordx4 v[206:207], off
	v_lshl_add_u64 v[206:207], v[208:209], 0, s[34:35]
	s_add_i32 m0, s44, 0x2000
	s_add_i32 s44, s65, s92
	global_load_lds_dwordx4 v[206:207], off
	s_mov_b32 m0, s44
	v_lshl_add_u64 v[206:207], v[210:211], 0, s[34:35]
	global_load_lds_dwordx4 v[206:207], off
	s_add_i32 m0, s44, 0x2000
	v_lshl_add_u64 v[206:207], v[232:233], 0, s[34:35]
	global_load_lds_dwordx4 v[206:207], off
	s_mov_b32 m0, s97
	v_lshl_add_u64 v[206:207], v[234:235], 0, s[34:35]
	global_load_lds_dwordx4 v[206:207], off
	s_mov_b32 m0, s98
	v_lshl_add_u64 v[206:207], v[236:237], 0, s[34:35]
	global_load_lds_dwordx4 v[206:207], off
	s_add_u32 s42, s42, 0x100
	s_addc_u32 s43, s43, 0
	s_add_u32 s17, s17, 0x100
	s_addc_u32 s60, s60, 0
	s_cmp_ge_u32 s61, s4
	s_mov_b32 s44, s61
	s_setprio 1
	s_waitcnt vmcnt(8) lgkmcnt(0)
	s_barrier
	v_mfma_f32_16x16x32_bf16 v[62:65], v[130:133], v[162:165], v[62:65]
	v_mfma_f32_16x16x32_bf16 v[54:57], v[138:141], v[162:165], v[54:57]
	v_mfma_f32_16x16x32_bf16 v[46:49], v[130:133], v[170:173], v[46:49]
	v_mfma_f32_16x16x32_bf16 v[38:41], v[138:141], v[170:173], v[38:41]
	v_mfma_f32_16x16x32_bf16 v[30:33], v[130:133], v[178:181], v[30:33]
	v_mfma_f32_16x16x32_bf16 v[22:25], v[138:141], v[178:181], v[22:25]
	v_mfma_f32_16x16x32_bf16 v[14:17], v[130:133], v[198:201], v[14:17]
	v_mfma_f32_16x16x32_bf16 v[6:9], v[138:141], v[198:201], v[6:9]
	v_mfma_f32_16x16x32_bf16 v[62:65], v[134:137], v[166:169], v[62:65]
	v_mfma_f32_16x16x32_bf16 v[54:57], v[142:145], v[166:169], v[54:57]
	v_mfma_f32_16x16x32_bf16 v[46:49], v[134:137], v[174:177], v[46:49]
	v_mfma_f32_16x16x32_bf16 v[38:41], v[142:145], v[174:177], v[38:41]
	v_mfma_f32_16x16x32_bf16 v[30:33], v[134:137], v[194:197], v[30:33]
	v_mfma_f32_16x16x32_bf16 v[22:25], v[142:145], v[194:197], v[22:25]
	v_mfma_f32_16x16x32_bf16 v[14:17], v[134:137], v[202:205], v[14:17]
	v_mfma_f32_16x16x32_bf16 v[6:9], v[142:145], v[202:205], v[6:9]
	v_mfma_f32_16x16x32_bf16 v[58:61], v[146:149], v[162:165], v[58:61]
	v_mfma_f32_16x16x32_bf16 v[50:53], v[154:157], v[162:165], v[50:53]
	v_mfma_f32_16x16x32_bf16 v[42:45], v[146:149], v[170:173], v[42:45]
	v_mfma_f32_16x16x32_bf16 v[34:37], v[154:157], v[170:173], v[34:37]
	v_mfma_f32_16x16x32_bf16 v[26:29], v[146:149], v[178:181], v[26:29]
	v_mfma_f32_16x16x32_bf16 v[18:21], v[154:157], v[178:181], v[18:21]
	v_mfma_f32_16x16x32_bf16 v[10:13], v[146:149], v[198:201], v[10:13]
	v_mfma_f32_16x16x32_bf16 v[2:5], v[154:157], v[198:201], v[2:5]
	v_mfma_f32_16x16x32_bf16 v[58:61], v[150:153], v[166:169], v[58:61]
	v_mfma_f32_16x16x32_bf16 v[50:53], v[158:161], v[166:169], v[50:53]
	v_mfma_f32_16x16x32_bf16 v[42:45], v[150:153], v[174:177], v[42:45]
	v_mfma_f32_16x16x32_bf16 v[34:37], v[158:161], v[174:177], v[34:37]
	v_mfma_f32_16x16x32_bf16 v[26:29], v[150:153], v[194:197], v[26:29]
	v_mfma_f32_16x16x32_bf16 v[18:21], v[158:161], v[194:197], v[18:21]
	v_mfma_f32_16x16x32_bf16 v[10:13], v[150:153], v[202:205], v[10:13]
	v_mfma_f32_16x16x32_bf16 v[2:5], v[158:161], v[202:205], v[2:5]
	s_barrier
	s_setprio 0
	s_cbranch_scc0 .LBB0_441
	s_and_b64 vcc, exec, s[36:37]
	s_cbranch_vccz .LBB0_445
	s_barrier
	s_cmp_lt_i32 s0, 2
	s_mov_b64 s[42:43], -1
	s_cbranch_scc0 .LBB0_446
